# GEMM unit headers: removed hipcc's redundant second zeroing of the 128 accumulators
# speedup vs baseline: 1.0073x; 1.0073x over previous
; template <class Epi, class Sched, bool ALIGN_EPI = false, bool SP2 = false>
; __device__ __forceinline__ void gemm_phase(PG8_LAS unsigned char* lds, const Gemm g, const Sched& S, const Epi& E, const int wid) {
;     ...
;     f32x4 acc[2][2][4][2];
; #pragma unroll
;     for (int a = 0; a < 2; ++a)
; #pragma unroll
;         for (int b = 0; b < 2; ++b)
; #pragma unroll
;             for (int m = 0; m < 4; ++m)
; #pragma unroll
;                 for (int n = 0; n < 2; ++n) acc[a][b][m][n] = (f32x4){0.f, 0.f, 0.f, 0.f};
;     ...
; #pragma unroll
;         for (int a = 0; a < 2; ++a)
; #pragma unroll
;             for (int b = 0; b < 2; ++b)
; #pragma unroll
;                 for (int m = 0; m < 4; ++m)
; #pragma unroll
;                     for (int n = 0; n < 2; ++n) acc[a][b][m][n] = (f32x4){0.f, 0.f, 0.f, 0.f};
;         cur = nxt; cA = nA; cB = nB; ++ui;
.LBB0_18:
	v_mov_b32_e32 v127, 0
	s_andn2_b64 vcc, exec, s[24:25]
	v_mov_b32_e32 v126, v127
	v_mov_b32_e32 v125, v127
	v_mov_b32_e32 v124, v127
	v_mov_b32_e32 v123, v127
	v_mov_b32_e32 v122, v127
	v_mov_b32_e32 v121, v127
	v_mov_b32_e32 v120, v127
	v_mov_b32_e32 v111, v127
	v_mov_b32_e32 v110, v127
	v_mov_b32_e32 v109, v127
	v_mov_b32_e32 v108, v127
	v_mov_b32_e32 v107, v127
	v_mov_b32_e32 v106, v127
	v_mov_b32_e32 v105, v127
	v_mov_b32_e32 v104, v127
	v_mov_b32_e32 v95, v127
	v_mov_b32_e32 v94, v127
	v_mov_b32_e32 v93, v127
	v_mov_b32_e32 v92, v127
	v_mov_b32_e32 v91, v127
	v_mov_b32_e32 v90, v127
	v_mov_b32_e32 v89, v127
	v_mov_b32_e32 v88, v127
	v_mov_b32_e32 v79, v127
	v_mov_b32_e32 v78, v127
	v_mov_b32_e32 v77, v127
	v_mov_b32_e32 v76, v127
	v_mov_b32_e32 v75, v127
	v_mov_b32_e32 v74, v127
	v_mov_b32_e32 v73, v127
	v_mov_b32_e32 v72, v127
	v_mov_b32_e32 v119, v127
	v_mov_b32_e32 v118, v127
	v_mov_b32_e32 v117, v127
	v_mov_b32_e32 v116, v127
	v_mov_b32_e32 v115, v127
	v_mov_b32_e32 v114, v127
	v_mov_b32_e32 v113, v127
	v_mov_b32_e32 v112, v127
	v_mov_b32_e32 v103, v127
	v_mov_b32_e32 v102, v127
	v_mov_b32_e32 v101, v127
	v_mov_b32_e32 v100, v127
	v_mov_b32_e32 v99, v127
	v_mov_b32_e32 v98, v127
	v_mov_b32_e32 v97, v127
	v_mov_b32_e32 v96, v127
	v_mov_b32_e32 v87, v127
	v_mov_b32_e32 v86, v127
	v_mov_b32_e32 v85, v127
	v_mov_b32_e32 v84, v127
	v_mov_b32_e32 v83, v127
	v_mov_b32_e32 v82, v127
	v_mov_b32_e32 v81, v127
	v_mov_b32_e32 v80, v127
	v_mov_b32_e32 v71, v127
	v_mov_b32_e32 v70, v127
	v_mov_b32_e32 v69, v127
	v_mov_b32_e32 v68, v127
	v_mov_b32_e32 v67, v127
	v_mov_b32_e32 v66, v127
	v_mov_b32_e32 v65, v127
	v_mov_b32_e32 v64, v127
	v_mov_b32_e32 v63, v127
	v_mov_b32_e32 v62, v127
	v_mov_b32_e32 v61, v127
	v_mov_b32_e32 v60, v127
	v_mov_b32_e32 v59, v127
	v_mov_b32_e32 v58, v127
	v_mov_b32_e32 v57, v127
	v_mov_b32_e32 v56, v127
	v_mov_b32_e32 v47, v127
	v_mov_b32_e32 v46, v127
	v_mov_b32_e32 v45, v127
	v_mov_b32_e32 v44, v127
	v_mov_b32_e32 v43, v127
	v_mov_b32_e32 v42, v127
	v_mov_b32_e32 v41, v127
	v_mov_b32_e32 v40, v127
	v_mov_b32_e32 v31, v127
	v_mov_b32_e32 v30, v127
	v_mov_b32_e32 v29, v127
	v_mov_b32_e32 v28, v127
	v_mov_b32_e32 v27, v127
	v_mov_b32_e32 v26, v127
	v_mov_b32_e32 v25, v127
	v_mov_b32_e32 v24, v127
	v_mov_b32_e32 v15, v127
	v_mov_b32_e32 v14, v127
	v_mov_b32_e32 v13, v127
	v_mov_b32_e32 v12, v127
	v_mov_b32_e32 v11, v127
	v_mov_b32_e32 v10, v127
	v_mov_b32_e32 v9, v127
	v_mov_b32_e32 v8, v127
	v_mov_b32_e32 v55, v127
	v_mov_b32_e32 v54, v127
	v_mov_b32_e32 v53, v127
	v_mov_b32_e32 v52, v127
	v_mov_b32_e32 v51, v127
	v_mov_b32_e32 v50, v127
	v_mov_b32_e32 v49, v127
	v_mov_b32_e32 v48, v127
	v_mov_b32_e32 v39, v127
	v_mov_b32_e32 v38, v127
	v_mov_b32_e32 v37, v127
	v_mov_b32_e32 v36, v127
	v_mov_b32_e32 v35, v127
	v_mov_b32_e32 v34, v127
	v_mov_b32_e32 v33, v127
	v_mov_b32_e32 v32, v127
	v_mov_b32_e32 v23, v127
	v_mov_b32_e32 v22, v127
	v_mov_b32_e32 v21, v127
	v_mov_b32_e32 v20, v127
	v_mov_b32_e32 v19, v127
	v_mov_b32_e32 v18, v127
	v_mov_b32_e32 v17, v127
	v_mov_b32_e32 v16, v127
	v_mov_b32_e32 v7, v127
	v_mov_b32_e32 v6, v127
	v_mov_b32_e32 v5, v127
	v_mov_b32_e32 v4, v127
	v_mov_b32_e32 v3, v127
	v_mov_b32_e32 v2, v127
	v_mov_b32_e32 v1, v127
	v_mov_b32_e32 v0, v127
	s_cbranch_vccnz .LBB0_21
	s_add_u32 s4, s38, 0x80
	s_addc_u32 s5, s39, 0
	s_add_u32 s0, s36, 0x100
	s_addc_u32 s1, s37, 0
	s_mov_b32 s36, 0

; template <class Epi, class Sched, bool ALIGN_EPI = false, bool SP2 = false>
; __device__ __forceinline__ void gemm_phase(PG8_LAS unsigned char* lds, const Gemm g, const Sched& S, const Epi& E, const int wid) {
;     ...
;     f32x4 acc[2][2][4][2];
; #pragma unroll
;     for (int a = 0; a < 2; ++a)
; #pragma unroll
;         for (int b = 0; b < 2; ++b)
; #pragma unroll
;             for (int m = 0; m < 4; ++m)
; #pragma unroll
;                 for (int n = 0; n < 2; ++n) acc[a][b][m][n] = (f32x4){0.f, 0.f, 0.f, 0.f};
;     ...
; #pragma unroll
;         for (int a = 0; a < 2; ++a)
; #pragma unroll
;             for (int b = 0; b < 2; ++b)
; #pragma unroll
;                 for (int m = 0; m < 4; ++m)
; #pragma unroll
;                     for (int n = 0; n < 2; ++n) acc[a][b][m][n] = (f32x4){0.f, 0.f, 0.f, 0.f};
;         cur = nxt; cA = nA; cB = nB; ++ui;
.LBB0_1098:
	v_mov_b32_e32 v143, 0
	s_andn2_b64 vcc, exec, s[28:29]
	v_mov_b32_e32 v142, v143
	v_mov_b32_e32 v141, v143
	v_mov_b32_e32 v140, v143
	v_mov_b32_e32 v139, v143
	v_mov_b32_e32 v138, v143
	v_mov_b32_e32 v137, v143
	v_mov_b32_e32 v136, v143
	v_mov_b32_e32 v127, v143
	v_mov_b32_e32 v126, v143
	v_mov_b32_e32 v125, v143
	v_mov_b32_e32 v124, v143
	v_mov_b32_e32 v123, v143
	v_mov_b32_e32 v122, v143
	v_mov_b32_e32 v121, v143
	v_mov_b32_e32 v120, v143
	v_mov_b32_e32 v111, v143
	v_mov_b32_e32 v110, v143
	v_mov_b32_e32 v109, v143
	v_mov_b32_e32 v108, v143
	v_mov_b32_e32 v107, v143
	v_mov_b32_e32 v106, v143
	v_mov_b32_e32 v105, v143
	v_mov_b32_e32 v104, v143
	v_mov_b32_e32 v95, v143
	v_mov_b32_e32 v94, v143
	v_mov_b32_e32 v93, v143
	v_mov_b32_e32 v92, v143
	v_mov_b32_e32 v91, v143
	v_mov_b32_e32 v90, v143
	v_mov_b32_e32 v89, v143
	v_mov_b32_e32 v88, v143
	v_mov_b32_e32 v135, v143
	v_mov_b32_e32 v134, v143
	v_mov_b32_e32 v133, v143
	v_mov_b32_e32 v132, v143
	v_mov_b32_e32 v131, v143
	v_mov_b32_e32 v130, v143
	v_mov_b32_e32 v129, v143
	v_mov_b32_e32 v128, v143
	v_mov_b32_e32 v119, v143
	v_mov_b32_e32 v118, v143
	v_mov_b32_e32 v117, v143
	v_mov_b32_e32 v116, v143
	v_mov_b32_e32 v115, v143
	v_mov_b32_e32 v114, v143
	v_mov_b32_e32 v113, v143
	v_mov_b32_e32 v112, v143
	v_mov_b32_e32 v103, v143
	v_mov_b32_e32 v102, v143
	v_mov_b32_e32 v101, v143
	v_mov_b32_e32 v100, v143
	v_mov_b32_e32 v99, v143
	v_mov_b32_e32 v98, v143
	v_mov_b32_e32 v97, v143
	v_mov_b32_e32 v96, v143
	v_mov_b32_e32 v87, v143
	v_mov_b32_e32 v86, v143
	v_mov_b32_e32 v85, v143
	v_mov_b32_e32 v84, v143
	v_mov_b32_e32 v83, v143
	v_mov_b32_e32 v82, v143
	v_mov_b32_e32 v81, v143
	v_mov_b32_e32 v80, v143
	v_mov_b32_e32 v79, v143
	v_mov_b32_e32 v78, v143
	v_mov_b32_e32 v77, v143
	v_mov_b32_e32 v76, v143
	v_mov_b32_e32 v75, v143
	v_mov_b32_e32 v74, v143
	v_mov_b32_e32 v73, v143
	v_mov_b32_e32 v72, v143
	v_mov_b32_e32 v51, v143
	v_mov_b32_e32 v50, v143
	v_mov_b32_e32 v49, v143
	v_mov_b32_e32 v48, v143
	v_mov_b32_e32 v43, v143
	v_mov_b32_e32 v42, v143
	v_mov_b32_e32 v41, v143
	v_mov_b32_e32 v40, v143
	v_mov_b32_e32 v31, v143
	v_mov_b32_e32 v30, v143
	v_mov_b32_e32 v29, v143
	v_mov_b32_e32 v28, v143
	v_mov_b32_e32 v27, v143
	v_mov_b32_e32 v26, v143
	v_mov_b32_e32 v25, v143
	v_mov_b32_e32 v24, v143
	v_mov_b32_e32 v15, v143
	v_mov_b32_e32 v14, v143
	v_mov_b32_e32 v13, v143
	v_mov_b32_e32 v12, v143
	v_mov_b32_e32 v11, v143
	v_mov_b32_e32 v10, v143
	v_mov_b32_e32 v9, v143
	v_mov_b32_e32 v8, v143
	v_mov_b32_e32 v67, v143
	v_mov_b32_e32 v66, v143
	v_mov_b32_e32 v65, v143
	v_mov_b32_e32 v64, v143
	v_mov_b32_e32 v59, v143
	v_mov_b32_e32 v58, v143
	v_mov_b32_e32 v57, v143
	v_mov_b32_e32 v56, v143
	v_mov_b32_e32 v39, v143
	v_mov_b32_e32 v38, v143
	v_mov_b32_e32 v37, v143
	v_mov_b32_e32 v36, v143
	v_mov_b32_e32 v35, v143
	v_mov_b32_e32 v34, v143
	v_mov_b32_e32 v33, v143
	v_mov_b32_e32 v32, v143
	v_mov_b32_e32 v23, v143
	v_mov_b32_e32 v22, v143
	v_mov_b32_e32 v21, v143
	v_mov_b32_e32 v20, v143
	v_mov_b32_e32 v19, v143
	v_mov_b32_e32 v18, v143
	v_mov_b32_e32 v17, v143
	v_mov_b32_e32 v16, v143
	v_mov_b32_e32 v7, v143
	v_mov_b32_e32 v6, v143
	v_mov_b32_e32 v5, v143
	v_mov_b32_e32 v4, v143
	v_mov_b32_e32 v3, v143
	v_mov_b32_e32 v2, v143
	v_mov_b32_e32 v1, v143
	v_mov_b32_e32 v0, v143
	s_cbranch_vccnz .LBB0_1101
	s_add_u32 s4, s8, 0x80
	s_addc_u32 s5, s9, 0
	s_add_u32 s0, s6, 0x100
	s_addc_u32 s1, s7, 0
	s_mov_b32 s6, 0

; template <class Epi, class Sched, bool ALIGN_EPI = false, bool SP2 = false>
; __device__ __forceinline__ void gemm_phase(PG8_LAS unsigned char* lds, const Gemm g, const Sched& S, const Epi& E, const int wid) {
;     ...
;     f32x4 acc[2][2][4][2];
; #pragma unroll
;     for (int a = 0; a < 2; ++a)
; #pragma unroll
;         for (int b = 0; b < 2; ++b)
; #pragma unroll
;             for (int m = 0; m < 4; ++m)
; #pragma unroll
;                 for (int n = 0; n < 2; ++n) acc[a][b][m][n] = (f32x4){0.f, 0.f, 0.f, 0.f};
;     ...
; #pragma unroll
;         for (int a = 0; a < 2; ++a)
; #pragma unroll
;             for (int b = 0; b < 2; ++b)
; #pragma unroll
;                 for (int m = 0; m < 4; ++m)
; #pragma unroll
;                     for (int n = 0; n < 2; ++n) acc[a][b][m][n] = (f32x4){0.f, 0.f, 0.f, 0.f};
;         cur = nxt; cA = nA; cB = nB; ++ui;
.LBB0_1177:
	v_mov_b32_e32 v127, 0
	s_andn2_b64 vcc, exec, s[20:21]
	v_mov_b32_e32 v126, v127
	v_mov_b32_e32 v125, v127
	v_mov_b32_e32 v124, v127
	v_mov_b32_e32 v123, v127
	v_mov_b32_e32 v122, v127
	v_mov_b32_e32 v121, v127
	v_mov_b32_e32 v120, v127
	v_mov_b32_e32 v111, v127
	v_mov_b32_e32 v110, v127
	v_mov_b32_e32 v109, v127
	v_mov_b32_e32 v108, v127
	v_mov_b32_e32 v107, v127
	v_mov_b32_e32 v106, v127
	v_mov_b32_e32 v105, v127
	v_mov_b32_e32 v104, v127
	v_mov_b32_e32 v95, v127
	v_mov_b32_e32 v94, v127
	v_mov_b32_e32 v93, v127
	v_mov_b32_e32 v92, v127
	v_mov_b32_e32 v91, v127
	v_mov_b32_e32 v90, v127
	v_mov_b32_e32 v89, v127
	v_mov_b32_e32 v88, v127
	v_mov_b32_e32 v79, v127
	v_mov_b32_e32 v78, v127
	v_mov_b32_e32 v77, v127
	v_mov_b32_e32 v76, v127
	v_mov_b32_e32 v75, v127
	v_mov_b32_e32 v74, v127
	v_mov_b32_e32 v73, v127
	v_mov_b32_e32 v72, v127
	v_mov_b32_e32 v119, v127
	v_mov_b32_e32 v118, v127
	v_mov_b32_e32 v117, v127
	v_mov_b32_e32 v116, v127
	v_mov_b32_e32 v115, v127
	v_mov_b32_e32 v114, v127
	v_mov_b32_e32 v113, v127
	v_mov_b32_e32 v112, v127
	v_mov_b32_e32 v103, v127
	v_mov_b32_e32 v102, v127
	v_mov_b32_e32 v101, v127
	v_mov_b32_e32 v100, v127
	v_mov_b32_e32 v99, v127
	v_mov_b32_e32 v98, v127
	v_mov_b32_e32 v97, v127
	v_mov_b32_e32 v96, v127
	v_mov_b32_e32 v87, v127
	v_mov_b32_e32 v86, v127
	v_mov_b32_e32 v85, v127
	v_mov_b32_e32 v84, v127
	v_mov_b32_e32 v83, v127
	v_mov_b32_e32 v82, v127
	v_mov_b32_e32 v81, v127
	v_mov_b32_e32 v80, v127
	v_mov_b32_e32 v71, v127
	v_mov_b32_e32 v70, v127
	v_mov_b32_e32 v69, v127
	v_mov_b32_e32 v68, v127
	v_mov_b32_e32 v67, v127
	v_mov_b32_e32 v66, v127
	v_mov_b32_e32 v65, v127
	v_mov_b32_e32 v64, v127
	v_mov_b32_e32 v63, v127
	v_mov_b32_e32 v62, v127
	v_mov_b32_e32 v61, v127
	v_mov_b32_e32 v60, v127
	v_mov_b32_e32 v59, v127
	v_mov_b32_e32 v58, v127
	v_mov_b32_e32 v57, v127
	v_mov_b32_e32 v56, v127
	v_mov_b32_e32 v47, v127
	v_mov_b32_e32 v46, v127
	v_mov_b32_e32 v45, v127
	v_mov_b32_e32 v44, v127
	v_mov_b32_e32 v43, v127
	v_mov_b32_e32 v42, v127
	v_mov_b32_e32 v41, v127
	v_mov_b32_e32 v40, v127
	v_mov_b32_e32 v31, v127
	v_mov_b32_e32 v30, v127
	v_mov_b32_e32 v29, v127
	v_mov_b32_e32 v28, v127
	v_mov_b32_e32 v27, v127
	v_mov_b32_e32 v26, v127
	v_mov_b32_e32 v25, v127
	v_mov_b32_e32 v24, v127
	v_mov_b32_e32 v15, v127
	v_mov_b32_e32 v14, v127
	v_mov_b32_e32 v13, v127
	v_mov_b32_e32 v12, v127
	v_mov_b32_e32 v11, v127
	v_mov_b32_e32 v10, v127
	v_mov_b32_e32 v9, v127
	v_mov_b32_e32 v8, v127
	v_mov_b32_e32 v55, v127
	v_mov_b32_e32 v54, v127
	v_mov_b32_e32 v53, v127
	v_mov_b32_e32 v52, v127
	v_mov_b32_e32 v51, v127
	v_mov_b32_e32 v50, v127
	v_mov_b32_e32 v49, v127
	v_mov_b32_e32 v48, v127
	v_mov_b32_e32 v39, v127
	v_mov_b32_e32 v38, v127
	v_mov_b32_e32 v37, v127
	v_mov_b32_e32 v36, v127
	v_mov_b32_e32 v35, v127
	v_mov_b32_e32 v34, v127
	v_mov_b32_e32 v33, v127
	v_mov_b32_e32 v32, v127
	v_mov_b32_e32 v23, v127
	v_mov_b32_e32 v22, v127
	v_mov_b32_e32 v21, v127
	v_mov_b32_e32 v20, v127
	v_mov_b32_e32 v19, v127
	v_mov_b32_e32 v18, v127
	v_mov_b32_e32 v17, v127
	v_mov_b32_e32 v16, v127
	v_mov_b32_e32 v7, v127
	v_mov_b32_e32 v6, v127
	v_mov_b32_e32 v5, v127
	v_mov_b32_e32 v4, v127
	v_mov_b32_e32 v3, v127
	v_mov_b32_e32 v2, v127
	v_mov_b32_e32 v1, v127
	v_mov_b32_e32 v0, v127
	s_cbranch_vccnz .LBB0_1180
	s_add_u32 s26, s26, 0x80
	s_addc_u32 s27, s27, 0
	s_add_u32 s0, s28, 0x100
	s_addc_u32 s1, s29, 0
	s_mov_b32 s28, 0

; template <class Epi, class Sched, bool ALIGN_EPI = false, bool SP2 = false>
; __device__ __forceinline__ void gemm_phase(PG8_LAS unsigned char* lds, const Gemm g, const Sched& S, const Epi& E, const int wid) {
;     ...
;     f32x4 acc[2][2][4][2];
; #pragma unroll
;     for (int a = 0; a < 2; ++a)
; #pragma unroll
;         for (int b = 0; b < 2; ++b)
; #pragma unroll
;             for (int m = 0; m < 4; ++m)
; #pragma unroll
;                 for (int n = 0; n < 2; ++n) acc[a][b][m][n] = (f32x4){0.f, 0.f, 0.f, 0.f};
;     ...
; #pragma unroll
;         for (int a = 0; a < 2; ++a)
; #pragma unroll
;             for (int b = 0; b < 2; ++b)
; #pragma unroll
;                 for (int m = 0; m < 4; ++m)
; #pragma unroll
;                     for (int n = 0; n < 2; ++n) acc[a][b][m][n] = (f32x4){0.f, 0.f, 0.f, 0.f};
;         cur = nxt; cA = nA; cB = nB; ++ui;
.LBB0_1256:
	v_mov_b32_e32 v127, 0
	s_andn2_b64 vcc, exec, s[20:21]
	v_mov_b32_e32 v126, v127
	v_mov_b32_e32 v125, v127
	v_mov_b32_e32 v124, v127
	v_mov_b32_e32 v123, v127
	v_mov_b32_e32 v122, v127
	v_mov_b32_e32 v121, v127
	v_mov_b32_e32 v120, v127
	v_mov_b32_e32 v111, v127
	v_mov_b32_e32 v110, v127
	v_mov_b32_e32 v109, v127
	v_mov_b32_e32 v108, v127
	v_mov_b32_e32 v107, v127
	v_mov_b32_e32 v106, v127
	v_mov_b32_e32 v105, v127
	v_mov_b32_e32 v104, v127
	v_mov_b32_e32 v95, v127
	v_mov_b32_e32 v94, v127
	v_mov_b32_e32 v93, v127
	v_mov_b32_e32 v92, v127
	v_mov_b32_e32 v91, v127
	v_mov_b32_e32 v90, v127
	v_mov_b32_e32 v89, v127
	v_mov_b32_e32 v88, v127
	v_mov_b32_e32 v79, v127
	v_mov_b32_e32 v78, v127
	v_mov_b32_e32 v77, v127
	v_mov_b32_e32 v76, v127
	v_mov_b32_e32 v75, v127
	v_mov_b32_e32 v74, v127
	v_mov_b32_e32 v73, v127
	v_mov_b32_e32 v72, v127
	v_mov_b32_e32 v119, v127
	v_mov_b32_e32 v118, v127
	v_mov_b32_e32 v117, v127
	v_mov_b32_e32 v116, v127
	v_mov_b32_e32 v115, v127
	v_mov_b32_e32 v114, v127
	v_mov_b32_e32 v113, v127
	v_mov_b32_e32 v112, v127
	v_mov_b32_e32 v103, v127
	v_mov_b32_e32 v102, v127
	v_mov_b32_e32 v101, v127
	v_mov_b32_e32 v100, v127
	v_mov_b32_e32 v99, v127
	v_mov_b32_e32 v98, v127
	v_mov_b32_e32 v97, v127
	v_mov_b32_e32 v96, v127
	v_mov_b32_e32 v87, v127
	v_mov_b32_e32 v86, v127
	v_mov_b32_e32 v85, v127
	v_mov_b32_e32 v84, v127
	v_mov_b32_e32 v83, v127
	v_mov_b32_e32 v82, v127
	v_mov_b32_e32 v81, v127
	v_mov_b32_e32 v80, v127
	v_mov_b32_e32 v71, v127
	v_mov_b32_e32 v70, v127
	v_mov_b32_e32 v69, v127
	v_mov_b32_e32 v68, v127
	v_mov_b32_e32 v67, v127
	v_mov_b32_e32 v66, v127
	v_mov_b32_e32 v65, v127
	v_mov_b32_e32 v64, v127
	v_mov_b32_e32 v63, v127
	v_mov_b32_e32 v62, v127
	v_mov_b32_e32 v61, v127
	v_mov_b32_e32 v60, v127
	v_mov_b32_e32 v59, v127
	v_mov_b32_e32 v58, v127
	v_mov_b32_e32 v57, v127
	v_mov_b32_e32 v56, v127
	v_mov_b32_e32 v47, v127
	v_mov_b32_e32 v46, v127
	v_mov_b32_e32 v45, v127
	v_mov_b32_e32 v44, v127
	v_mov_b32_e32 v43, v127
	v_mov_b32_e32 v42, v127
	v_mov_b32_e32 v41, v127
	v_mov_b32_e32 v40, v127
	v_mov_b32_e32 v31, v127
	v_mov_b32_e32 v30, v127
	v_mov_b32_e32 v29, v127
	v_mov_b32_e32 v28, v127
	v_mov_b32_e32 v27, v127
	v_mov_b32_e32 v26, v127
	v_mov_b32_e32 v25, v127
	v_mov_b32_e32 v24, v127
	v_mov_b32_e32 v15, v127
	v_mov_b32_e32 v14, v127
	v_mov_b32_e32 v13, v127
	v_mov_b32_e32 v12, v127
	v_mov_b32_e32 v11, v127
	v_mov_b32_e32 v10, v127
	v_mov_b32_e32 v9, v127
	v_mov_b32_e32 v8, v127
	v_mov_b32_e32 v55, v127
	v_mov_b32_e32 v54, v127
	v_mov_b32_e32 v53, v127
	v_mov_b32_e32 v52, v127
	v_mov_b32_e32 v51, v127
	v_mov_b32_e32 v50, v127
	v_mov_b32_e32 v49, v127
	v_mov_b32_e32 v48, v127
	v_mov_b32_e32 v39, v127
	v_mov_b32_e32 v38, v127
	v_mov_b32_e32 v37, v127
	v_mov_b32_e32 v36, v127
	v_mov_b32_e32 v35, v127
	v_mov_b32_e32 v34, v127
	v_mov_b32_e32 v33, v127
	v_mov_b32_e32 v32, v127
	v_mov_b32_e32 v23, v127
	v_mov_b32_e32 v22, v127
	v_mov_b32_e32 v21, v127
	v_mov_b32_e32 v20, v127
	v_mov_b32_e32 v19, v127
	v_mov_b32_e32 v18, v127
	v_mov_b32_e32 v17, v127
	v_mov_b32_e32 v16, v127
	v_mov_b32_e32 v7, v127
	v_mov_b32_e32 v6, v127
	v_mov_b32_e32 v5, v127
	v_mov_b32_e32 v4, v127
	v_mov_b32_e32 v3, v127
	v_mov_b32_e32 v2, v127
	v_mov_b32_e32 v1, v127
	v_mov_b32_e32 v0, v127
	s_cbranch_vccnz .LBB0_1259
	s_add_u32 s28, s28, 0x80
	s_addc_u32 s29, s29, 0
	s_add_u32 s0, s30, 0x100
	s_addc_u32 s1, s31, 0
	s_mov_b32 s30, 0

; template <class Epi, class Sched, bool ALIGN_EPI = false, bool SP2 = false>
; __device__ __forceinline__ void gemm_phase(PG8_LAS unsigned char* lds, const Gemm g, const Sched& S, const Epi& E, const int wid) {
;     ...
;     f32x4 acc[2][2][4][2];
; #pragma unroll
;     for (int a = 0; a < 2; ++a)
; #pragma unroll
;         for (int b = 0; b < 2; ++b)
; #pragma unroll
;             for (int m = 0; m < 4; ++m)
; #pragma unroll
;                 for (int n = 0; n < 2; ++n) acc[a][b][m][n] = (f32x4){0.f, 0.f, 0.f, 0.f};
;     ...
; #pragma unroll
;         for (int a = 0; a < 2; ++a)
; #pragma unroll
;             for (int b = 0; b < 2; ++b)
; #pragma unroll
;                 for (int m = 0; m < 4; ++m)
; #pragma unroll
;                     for (int n = 0; n < 2; ++n) acc[a][b][m][n] = (f32x4){0.f, 0.f, 0.f, 0.f};
;         cur = nxt; cA = nA; cB = nB; ++ui;
.LBB0_1337:
	v_mov_b32_e32 v123, 0
	s_andn2_b64 vcc, exec, s[24:25]
	v_mov_b32_e32 v122, v123
	v_mov_b32_e32 v121, v123
	v_mov_b32_e32 v120, v123
	v_mov_b32_e32 v127, v123
	v_mov_b32_e32 v126, v123
	v_mov_b32_e32 v125, v123
	v_mov_b32_e32 v124, v123
	v_mov_b32_e32 v111, v123
	v_mov_b32_e32 v110, v123
	v_mov_b32_e32 v109, v123
	v_mov_b32_e32 v108, v123
	v_mov_b32_e32 v107, v123
	v_mov_b32_e32 v106, v123
	v_mov_b32_e32 v105, v123
	v_mov_b32_e32 v104, v123
	v_mov_b32_e32 v95, v123
	v_mov_b32_e32 v94, v123
	v_mov_b32_e32 v93, v123
	v_mov_b32_e32 v92, v123
	v_mov_b32_e32 v91, v123
	v_mov_b32_e32 v90, v123
	v_mov_b32_e32 v89, v123
	v_mov_b32_e32 v88, v123
	v_mov_b32_e32 v79, v123
	v_mov_b32_e32 v78, v123
	v_mov_b32_e32 v77, v123
	v_mov_b32_e32 v76, v123
	v_mov_b32_e32 v75, v123
	v_mov_b32_e32 v74, v123
	v_mov_b32_e32 v73, v123
	v_mov_b32_e32 v72, v123
	v_mov_b32_e32 v119, v123
	v_mov_b32_e32 v118, v123
	v_mov_b32_e32 v117, v123
	v_mov_b32_e32 v116, v123
	v_mov_b32_e32 v115, v123
	v_mov_b32_e32 v114, v123
	v_mov_b32_e32 v113, v123
	v_mov_b32_e32 v112, v123
	v_mov_b32_e32 v103, v123
	v_mov_b32_e32 v102, v123
	v_mov_b32_e32 v101, v123
	v_mov_b32_e32 v100, v123
	v_mov_b32_e32 v99, v123
	v_mov_b32_e32 v98, v123
	v_mov_b32_e32 v97, v123
	v_mov_b32_e32 v96, v123
	v_mov_b32_e32 v87, v123
	v_mov_b32_e32 v86, v123
	v_mov_b32_e32 v85, v123
	v_mov_b32_e32 v84, v123
	v_mov_b32_e32 v83, v123
	v_mov_b32_e32 v82, v123
	v_mov_b32_e32 v81, v123
	v_mov_b32_e32 v80, v123
	v_mov_b32_e32 v71, v123
	v_mov_b32_e32 v70, v123
	v_mov_b32_e32 v69, v123
	v_mov_b32_e32 v68, v123
	v_mov_b32_e32 v67, v123
	v_mov_b32_e32 v66, v123
	v_mov_b32_e32 v65, v123
	v_mov_b32_e32 v64, v123
	v_mov_b32_e32 v63, v123
	v_mov_b32_e32 v62, v123
	v_mov_b32_e32 v61, v123
	v_mov_b32_e32 v60, v123
	v_mov_b32_e32 v59, v123
	v_mov_b32_e32 v58, v123
	v_mov_b32_e32 v57, v123
	v_mov_b32_e32 v56, v123
	v_mov_b32_e32 v47, v123
	v_mov_b32_e32 v46, v123
	v_mov_b32_e32 v45, v123
	v_mov_b32_e32 v44, v123
	v_mov_b32_e32 v43, v123
	v_mov_b32_e32 v42, v123
	v_mov_b32_e32 v41, v123
	v_mov_b32_e32 v40, v123
	v_mov_b32_e32 v31, v123
	v_mov_b32_e32 v30, v123
	v_mov_b32_e32 v29, v123
	v_mov_b32_e32 v28, v123
	v_mov_b32_e32 v27, v123
	v_mov_b32_e32 v26, v123
	v_mov_b32_e32 v25, v123
	v_mov_b32_e32 v24, v123
	v_mov_b32_e32 v15, v123
	v_mov_b32_e32 v14, v123
	v_mov_b32_e32 v13, v123
	v_mov_b32_e32 v12, v123
	v_mov_b32_e32 v11, v123
	v_mov_b32_e32 v10, v123
	v_mov_b32_e32 v9, v123
	v_mov_b32_e32 v8, v123
	v_mov_b32_e32 v55, v123
	v_mov_b32_e32 v54, v123
	v_mov_b32_e32 v53, v123
	v_mov_b32_e32 v52, v123
	v_mov_b32_e32 v51, v123
	v_mov_b32_e32 v50, v123
	v_mov_b32_e32 v49, v123
	v_mov_b32_e32 v48, v123
	v_mov_b32_e32 v39, v123
	v_mov_b32_e32 v38, v123
	v_mov_b32_e32 v37, v123
	v_mov_b32_e32 v36, v123
	v_mov_b32_e32 v35, v123
	v_mov_b32_e32 v34, v123
	v_mov_b32_e32 v33, v123
	v_mov_b32_e32 v32, v123
	v_mov_b32_e32 v23, v123
	v_mov_b32_e32 v22, v123
	v_mov_b32_e32 v21, v123
	v_mov_b32_e32 v20, v123
	v_mov_b32_e32 v19, v123
	v_mov_b32_e32 v18, v123
	v_mov_b32_e32 v17, v123
	v_mov_b32_e32 v16, v123
	v_mov_b32_e32 v7, v123
	v_mov_b32_e32 v6, v123
	v_mov_b32_e32 v5, v123
	v_mov_b32_e32 v4, v123
	v_mov_b32_e32 v3, v123
	v_mov_b32_e32 v2, v123
	s_waitcnt lgkmcnt(0)
	v_mov_b32_e32 v1, v123
	v_mov_b32_e32 v0, v123
	s_cbranch_vccnz .LBB0_1340
	s_add_u32 s4, s36, 0x80
	s_addc_u32 s5, s37, 0
	s_add_u32 s0, s34, 0x100
	s_addc_u32 s1, s35, 0
	s_mov_b32 s34, 0

; template <class Epi, class Sched, bool ALIGN_EPI = false, bool SP2 = false>
; __device__ __forceinline__ void gemm_phase(PG8_LAS unsigned char* lds, const Gemm g, const Sched& S, const Epi& E, const int wid) {
;     ...
;     f32x4 acc[2][2][4][2];
; #pragma unroll
;     for (int a = 0; a < 2; ++a)
; #pragma unroll
;         for (int b = 0; b < 2; ++b)
; #pragma unroll
;             for (int m = 0; m < 4; ++m)
; #pragma unroll
;                 for (int n = 0; n < 2; ++n) acc[a][b][m][n] = (f32x4){0.f, 0.f, 0.f, 0.f};
;     ...
; #pragma unroll
;         for (int a = 0; a < 2; ++a)
; #pragma unroll
;             for (int b = 0; b < 2; ++b)
; #pragma unroll
;                 for (int m = 0; m < 4; ++m)
; #pragma unroll
;                     for (int n = 0; n < 2; ++n) acc[a][b][m][n] = (f32x4){0.f, 0.f, 0.f, 0.f};
;         cur = nxt; cA = nA; cB = nB; ++ui;
.LBB0_1493:
	v_mov_b32_e32 v123, 0
	s_andn2_b64 vcc, exec, s[22:23]
	v_mov_b32_e32 v122, v123
	v_mov_b32_e32 v121, v123
	v_mov_b32_e32 v120, v123
	v_mov_b32_e32 v115, v123
	v_mov_b32_e32 v114, v123
	v_mov_b32_e32 v113, v123
	v_mov_b32_e32 v112, v123
	v_mov_b32_e32 v107, v123
	v_mov_b32_e32 v106, v123
	v_mov_b32_e32 v105, v123
	v_mov_b32_e32 v104, v123
	v_mov_b32_e32 v99, v123
	v_mov_b32_e32 v98, v123
	v_mov_b32_e32 v97, v123
	v_mov_b32_e32 v96, v123
	v_mov_b32_e32 v91, v123
	v_mov_b32_e32 v90, v123
	v_mov_b32_e32 v89, v123
	v_mov_b32_e32 v88, v123
	v_mov_b32_e32 v83, v123
	v_mov_b32_e32 v82, v123
	v_mov_b32_e32 v81, v123
	v_mov_b32_e32 v80, v123
	v_mov_b32_e32 v75, v123
	v_mov_b32_e32 v74, v123
	v_mov_b32_e32 v73, v123
	v_mov_b32_e32 v72, v123
	v_mov_b32_e32 v67, v123
	v_mov_b32_e32 v66, v123
	v_mov_b32_e32 v65, v123
	v_mov_b32_e32 v64, v123
	v_mov_b32_e32 v127, v123
	v_mov_b32_e32 v126, v123
	v_mov_b32_e32 v125, v123
	v_mov_b32_e32 v124, v123
	v_mov_b32_e32 v119, v123
	v_mov_b32_e32 v118, v123
	v_mov_b32_e32 v117, v123
	v_mov_b32_e32 v116, v123
	v_mov_b32_e32 v111, v123
	v_mov_b32_e32 v110, v123
	v_mov_b32_e32 v109, v123
	v_mov_b32_e32 v108, v123
	v_mov_b32_e32 v103, v123
	v_mov_b32_e32 v102, v123
	v_mov_b32_e32 v101, v123
	v_mov_b32_e32 v100, v123
	v_mov_b32_e32 v95, v123
	v_mov_b32_e32 v94, v123
	v_mov_b32_e32 v93, v123
	v_mov_b32_e32 v92, v123
	v_mov_b32_e32 v87, v123
	v_mov_b32_e32 v86, v123
	v_mov_b32_e32 v85, v123
	v_mov_b32_e32 v84, v123
	v_mov_b32_e32 v79, v123
	v_mov_b32_e32 v78, v123
	v_mov_b32_e32 v77, v123
	v_mov_b32_e32 v76, v123
	v_mov_b32_e32 v71, v123
	v_mov_b32_e32 v70, v123
	v_mov_b32_e32 v69, v123
	v_mov_b32_e32 v68, v123
	v_mov_b32_e32 v59, v123
	v_mov_b32_e32 v58, v123
	v_mov_b32_e32 v57, v123
	v_mov_b32_e32 v56, v123
	v_mov_b32_e32 v51, v123
	v_mov_b32_e32 v50, v123
	v_mov_b32_e32 v49, v123
	v_mov_b32_e32 v48, v123
	v_mov_b32_e32 v43, v123
	v_mov_b32_e32 v42, v123
	v_mov_b32_e32 v41, v123
	v_mov_b32_e32 v40, v123
	v_mov_b32_e32 v35, v123
	v_mov_b32_e32 v34, v123
	v_mov_b32_e32 v33, v123
	v_mov_b32_e32 v32, v123
	v_mov_b32_e32 v27, v123
	v_mov_b32_e32 v26, v123
	v_mov_b32_e32 v25, v123
	v_mov_b32_e32 v24, v123
	v_mov_b32_e32 v19, v123
	v_mov_b32_e32 v18, v123
	v_mov_b32_e32 v17, v123
	v_mov_b32_e32 v16, v123
	v_mov_b32_e32 v11, v123
	v_mov_b32_e32 v10, v123
	v_mov_b32_e32 v9, v123
	v_mov_b32_e32 v8, v123
	v_mov_b32_e32 v7, v123
	v_mov_b32_e32 v6, v123
	v_mov_b32_e32 v5, v123
	v_mov_b32_e32 v4, v123
	v_mov_b32_e32 v63, v123
	v_mov_b32_e32 v62, v123
	v_mov_b32_e32 v61, v123
	v_mov_b32_e32 v60, v123
	v_mov_b32_e32 v55, v123
	v_mov_b32_e32 v54, v123
	v_mov_b32_e32 v53, v123
	v_mov_b32_e32 v52, v123
	v_mov_b32_e32 v47, v123
	v_mov_b32_e32 v46, v123
	v_mov_b32_e32 v45, v123
	v_mov_b32_e32 v44, v123
	v_mov_b32_e32 v39, v123
	v_mov_b32_e32 v38, v123
	v_mov_b32_e32 v37, v123
	v_mov_b32_e32 v36, v123
	v_mov_b32_e32 v31, v123
	v_mov_b32_e32 v30, v123
	v_mov_b32_e32 v29, v123
	v_mov_b32_e32 v28, v123
	v_mov_b32_e32 v23, v123
	v_mov_b32_e32 v22, v123
	v_mov_b32_e32 v21, v123
	v_mov_b32_e32 v20, v123
	v_mov_b32_e32 v15, v123
	v_mov_b32_e32 v14, v123
	v_mov_b32_e32 v13, v123
	v_mov_b32_e32 v12, v123
	v_mov_b32_e32 v3, v123
	v_mov_b32_e32 v2, v123
	v_mov_b32_e32 v1, v123
	v_mov_b32_e32 v0, v123
	s_cbranch_vccnz .LBB0_1496
	s_add_u32 s4, s8, 0x80
	s_addc_u32 s5, s9, 0
	s_add_u32 s0, s6, 0x100
	s_addc_u32 s1, s7, 0
	s_mov_b32 s6, 0

; template <class Epi, class Sched, bool ALIGN_EPI = false, bool SP2 = false>
; __device__ __forceinline__ void gemm_phase(PG8_LAS unsigned char* lds, const Gemm g, const Sched& S, const Epi& E, const int wid) {
;     ...
;     f32x4 acc[2][2][4][2];
; #pragma unroll
;     for (int a = 0; a < 2; ++a)
; #pragma unroll
;         for (int b = 0; b < 2; ++b)
; #pragma unroll
;             for (int m = 0; m < 4; ++m)
; #pragma unroll
;                 for (int n = 0; n < 2; ++n) acc[a][b][m][n] = (f32x4){0.f, 0.f, 0.f, 0.f};
;     ...
; #pragma unroll
;         for (int a = 0; a < 2; ++a)
; #pragma unroll
;             for (int b = 0; b < 2; ++b)
; #pragma unroll
;                 for (int m = 0; m < 4; ++m)
; #pragma unroll
;                     for (int n = 0; n < 2; ++n) acc[a][b][m][n] = (f32x4){0.f, 0.f, 0.f, 0.f};
;         cur = nxt; cA = nA; cB = nB; ++ui;
.LBB0_1572:
	v_mov_b32_e32 v127, 0
	s_andn2_b64 vcc, exec, s[18:19]
	v_mov_b32_e32 v126, v127
	v_mov_b32_e32 v125, v127
	v_mov_b32_e32 v124, v127
	v_mov_b32_e32 v123, v127
	v_mov_b32_e32 v122, v127
	v_mov_b32_e32 v121, v127
	v_mov_b32_e32 v120, v127
	v_mov_b32_e32 v111, v127
	v_mov_b32_e32 v110, v127
	v_mov_b32_e32 v109, v127
	v_mov_b32_e32 v108, v127
	v_mov_b32_e32 v107, v127
	v_mov_b32_e32 v106, v127
	v_mov_b32_e32 v105, v127
	v_mov_b32_e32 v104, v127
	v_mov_b32_e32 v95, v127
	v_mov_b32_e32 v94, v127
	v_mov_b32_e32 v93, v127
	v_mov_b32_e32 v92, v127
	v_mov_b32_e32 v91, v127
	v_mov_b32_e32 v90, v127
	v_mov_b32_e32 v89, v127
	v_mov_b32_e32 v88, v127
	v_mov_b32_e32 v79, v127
	v_mov_b32_e32 v78, v127
	v_mov_b32_e32 v77, v127
	v_mov_b32_e32 v76, v127
	v_mov_b32_e32 v75, v127
	v_mov_b32_e32 v74, v127
	v_mov_b32_e32 v73, v127
	v_mov_b32_e32 v72, v127
	v_mov_b32_e32 v119, v127
	v_mov_b32_e32 v118, v127
	v_mov_b32_e32 v117, v127
	v_mov_b32_e32 v116, v127
	v_mov_b32_e32 v115, v127
	v_mov_b32_e32 v114, v127
	v_mov_b32_e32 v113, v127
	v_mov_b32_e32 v112, v127
	v_mov_b32_e32 v103, v127
	v_mov_b32_e32 v102, v127
	v_mov_b32_e32 v101, v127
	v_mov_b32_e32 v100, v127
	v_mov_b32_e32 v99, v127
	v_mov_b32_e32 v98, v127
	v_mov_b32_e32 v97, v127
	v_mov_b32_e32 v96, v127
	v_mov_b32_e32 v87, v127
	v_mov_b32_e32 v86, v127
	v_mov_b32_e32 v85, v127
	v_mov_b32_e32 v84, v127
	v_mov_b32_e32 v83, v127
	v_mov_b32_e32 v82, v127
	v_mov_b32_e32 v81, v127
	v_mov_b32_e32 v80, v127
	v_mov_b32_e32 v71, v127
	v_mov_b32_e32 v70, v127
	v_mov_b32_e32 v69, v127
	v_mov_b32_e32 v68, v127
	v_mov_b32_e32 v67, v127
	v_mov_b32_e32 v66, v127
	v_mov_b32_e32 v65, v127
	v_mov_b32_e32 v64, v127
	v_mov_b32_e32 v63, v127
	v_mov_b32_e32 v62, v127
	v_mov_b32_e32 v61, v127
	v_mov_b32_e32 v60, v127
	v_mov_b32_e32 v59, v127
	v_mov_b32_e32 v58, v127
	v_mov_b32_e32 v57, v127
	v_mov_b32_e32 v56, v127
	v_mov_b32_e32 v47, v127
	v_mov_b32_e32 v46, v127
	v_mov_b32_e32 v45, v127
	v_mov_b32_e32 v44, v127
	v_mov_b32_e32 v43, v127
	v_mov_b32_e32 v42, v127
	v_mov_b32_e32 v41, v127
	v_mov_b32_e32 v40, v127
	v_mov_b32_e32 v31, v127
	v_mov_b32_e32 v30, v127
	v_mov_b32_e32 v29, v127
	v_mov_b32_e32 v28, v127
	v_mov_b32_e32 v27, v127
	v_mov_b32_e32 v26, v127
	v_mov_b32_e32 v25, v127
	v_mov_b32_e32 v24, v127
	v_mov_b32_e32 v15, v127
	v_mov_b32_e32 v14, v127
	v_mov_b32_e32 v13, v127
	v_mov_b32_e32 v12, v127
	v_mov_b32_e32 v11, v127
	v_mov_b32_e32 v10, v127
	v_mov_b32_e32 v9, v127
	v_mov_b32_e32 v8, v127
	v_mov_b32_e32 v55, v127
	v_mov_b32_e32 v54, v127
	v_mov_b32_e32 v53, v127
	v_mov_b32_e32 v52, v127
	v_mov_b32_e32 v51, v127
	v_mov_b32_e32 v50, v127
	v_mov_b32_e32 v49, v127
	v_mov_b32_e32 v48, v127
	v_mov_b32_e32 v39, v127
	v_mov_b32_e32 v38, v127
	v_mov_b32_e32 v37, v127
	v_mov_b32_e32 v36, v127
	v_mov_b32_e32 v35, v127
	v_mov_b32_e32 v34, v127
	v_mov_b32_e32 v33, v127
	v_mov_b32_e32 v32, v127
	v_mov_b32_e32 v23, v127
	v_mov_b32_e32 v22, v127
	v_mov_b32_e32 v21, v127
	v_mov_b32_e32 v20, v127
	v_mov_b32_e32 v19, v127
	v_mov_b32_e32 v18, v127
	v_mov_b32_e32 v17, v127
	v_mov_b32_e32 v16, v127
	v_mov_b32_e32 v7, v127
	v_mov_b32_e32 v6, v127
	v_mov_b32_e32 v5, v127
	v_mov_b32_e32 v4, v127
	v_mov_b32_e32 v3, v127
	v_mov_b32_e32 v2, v127
	v_mov_b32_e32 v1, v127
	v_mov_b32_e32 v0, v127
	s_cbranch_vccnz .LBB0_1575
	s_add_u32 s40, s40, 0x80
	s_addc_u32 s41, s41, 0
	s_add_u32 s73, s42, 0x100
	s_addc_u32 s74, s43, 0
	s_mov_b32 s42, 0
